# fp8 GEMM loops: v_mfma_f32_16x16x128_f8f6f4 instead of the scale form with unit (E8M0 127) scales - same operands, same results, 8-byte encoding
# speedup vs baseline: 1.0028x; 1.0028x over previous
; #define PG8_STAGE(bufoff, gbase, voff) do { _Pragma("unroll") for (int _i = 0; _i < 2; ++_i) \
;         __builtin_amdgcn_global_load_lds((const unsigned*)((const char*)(gbase) + (voff)[_i]), (LAS unsigned*)(lds + (bufoff) + ldsw + _i * 8192), 16, 0, 0); } while (0)
; #define PG8_WAIT_V(n) asm volatile("s_waitcnt vmcnt(" #n ")" ::: "memory")
; #define PG8_WAIT_L(n) asm volatile("s_waitcnt lgkmcnt(" #n ")" ::: "memory")
; #define PG8_BAR __builtin_amdgcn_s_barrier()
; #define PG8_SCHED __builtin_amdgcn_sched_barrier(0)
; template <class Epi, class Sched, bool FP8 = false>
; __device__ __forceinline__ void gemm_phase(LAS unsigned char* lds, const Gemm g, const Sched& S, const Epi& E) {
;     ...
;             PG8_LDB(B0, 0, 0); PG8_LDB(B1, 0, 1); PG8_SCHED; PG8_LDA(At, 0, 0); PG8_STAGE(PG8_SA(1, 1), a1 + hstepA, voffA);
;             PG8_WAIT_V(8); PG8_WAIT_L(0); PG8_BAR; PG8_MMA(0, 0, At, B0); PG8_MMA(0, 1, At, B1); PG8_BAR; PG8_SCHED;
;             PG8_LDA(At, 0, 1); PG8_STAGE(PG8_SB(0, 0), b2, voffB); PG8_STAGE(PG8_SB(0, 1), b2 + hstepB, voffB); PG8_STAGE(PG8_SA(0, 0), a2, voffA);
;             PG8_WAIT_V(8); PG8_WAIT_L(0); PG8_BAR; PG8_MMA(1, 0, At, B0); PG8_MMA(1, 1, At, B1); PG8_BAR; PG8_SCHED;
.LBB0_74:
	ds_read_b128 v[16:19], v165
	ds_read_b128 v[20:23], v165 offset:1024
	ds_read_b128 v[24:27], v165 offset:2048
	ds_read_b128 v[28:31], v165 offset:3072
	ds_read_b128 v[0:3], v193
	ds_read_b128 v[4:7], v193 offset:1024
	ds_read_b128 v[8:11], v193 offset:2048
	ds_read_b128 v[12:15], v193 offset:3072
	s_add_u32 s10, s6, 0xfffc0080
	s_addc_u32 s11, s7, -1
	s_cmp_eq_u32 s44, 12
	s_cselect_b32 s43, s1, s11
	s_cselect_b32 s42, s9, s10
	s_cselect_b32 s11, s16, s37
	s_cselect_b32 s10, s33, s35
	v_lshl_add_u64 v[224:225], s[6:7], 0, v[176:177]
	s_add_i32 m0, s48, 0xc000
	ds_read_b128 v[184:187], v194
	ds_read_b128 v[188:191], v194 offset:1024
	ds_read_b128 v[200:203], v194 offset:2048
	ds_read_b128 v[204:207], v194 offset:3072
	ds_read_b128 v[208:211], v194 offset:4096
	ds_read_b128 v[212:215], v194 offset:5120
	ds_read_b128 v[216:219], v194 offset:6144
	ds_read_b128 v[220:223], v194 offset:7168
	global_load_lds_dwordx4 v[224:225], off
	v_lshl_add_u64 v[224:225], s[6:7], 0, v[178:179]
	s_add_i32 m0, s48, 0xe000
	s_nop 0
	global_load_lds_dwordx4 v[224:225], off
	s_waitcnt vmcnt(8)
	s_waitcnt lgkmcnt(0)
	s_barrier
	s_setprio 1
	s_waitcnt lgkmcnt(0)
	v_mfma_f32_16x16x128_f8f6f4 v[156:159], v[16:23], v[184:191], v[156:159]
	v_mfma_f32_16x16x128_f8f6f4 v[148:151], v[24:31], v[184:191], v[148:151]
	v_mfma_f32_16x16x128_f8f6f4 v[140:143], v[16:23], v[200:207], v[140:143]
	v_mfma_f32_16x16x128_f8f6f4 v[136:139], v[24:31], v[200:207], v[136:139]
	v_mfma_f32_16x16x128_f8f6f4 v[124:127], v[16:23], v[208:215], v[124:127]
	v_mfma_f32_16x16x128_f8f6f4 v[120:123], v[24:31], v[208:215], v[120:123]
	v_mfma_f32_16x16x128_f8f6f4 v[108:111], v[16:23], v[216:223], v[108:111]
	v_mfma_f32_16x16x128_f8f6f4 v[104:107], v[24:31], v[216:223], v[104:107]
	s_setprio 0
	s_setprio 1
	v_mfma_f32_16x16x128_f8f6f4 v[152:155], v[0:7], v[184:191], v[152:155]
	v_mfma_f32_16x16x128_f8f6f4 v[144:147], v[8:15], v[184:191], v[144:147]
	v_mfma_f32_16x16x128_f8f6f4 v[132:135], v[0:7], v[200:207], v[132:135]
	v_mfma_f32_16x16x128_f8f6f4 v[128:131], v[8:15], v[200:207], v[128:131]
	v_mfma_f32_16x16x128_f8f6f4 v[116:119], v[0:7], v[208:215], v[116:119]
	v_mfma_f32_16x16x128_f8f6f4 v[112:115], v[8:15], v[208:215], v[112:115]
	v_mfma_f32_16x16x128_f8f6f4 v[100:103], v[0:7], v[216:223], v[100:103]
	v_mfma_f32_16x16x128_f8f6f4 v[96:99], v[8:15], v[216:223], v[96:99]
	s_setprio 0
	s_barrier
	s_add_i32 s45, s62, s47
	v_lshl_add_u64 v[184:185], s[10:11], 0, v[168:169]
	s_mov_b32 m0, s45
	ds_read_b128 v[200:203], v194 offset:16384
	ds_read_b128 v[204:207], v194 offset:17408
	ds_read_b128 v[208:211], v194 offset:18432
	ds_read_b128 v[212:215], v194 offset:19456
	ds_read_b128 v[216:219], v194 offset:20480
	ds_read_b128 v[220:223], v194 offset:21504
	ds_read_b128 v[224:227], v194 offset:22528
	ds_read_b128 v[228:231], v194 offset:23552
	global_load_lds_dwordx4 v[184:185], off
	s_add_i32 m0, s45, 0x2000
	s_add_u32 s68, s10, 0x80000
	v_lshl_add_u64 v[186:187], s[10:11], 0, v[172:173]
	s_addc_u32 s69, s11, 0
	s_add_i32 s45, s63, s47
	global_load_lds_dwordx4 v[186:187], off
	v_lshl_add_u64 v[188:189], s[68:69], 0, v[168:169]
	s_mov_b32 m0, s45
	v_lshl_add_u64 v[190:191], s[42:43], 0, v[170:171]
	global_load_lds_dwordx4 v[188:189], off
	v_lshl_add_u64 v[188:189], s[68:69], 0, v[172:173]
	s_add_i32 m0, s45, 0x2000
	s_nop 0
	global_load_lds_dwordx4 v[188:189], off
	v_lshl_add_u64 v[188:189], s[42:43], 0, v[166:167]
	s_mov_b32 m0, s48
	s_nop 0
	global_load_lds_dwordx4 v[188:189], off
	s_mov_b32 m0, s49
	s_nop 0
	global_load_lds_dwordx4 v[190:191], off
	s_waitcnt vmcnt(8)
	s_waitcnt lgkmcnt(0)
	s_barrier
	s_setprio 1
	s_waitcnt lgkmcnt(0)
	v_mfma_f32_16x16x128_f8f6f4 v[92:95], v[16:23], v[200:207], v[92:95]
	v_mfma_f32_16x16x128_f8f6f4 v[88:91], v[24:31], v[200:207], v[88:91]
	v_mfma_f32_16x16x128_f8f6f4 v[76:79], v[16:23], v[208:215], v[76:79]
	v_mfma_f32_16x16x128_f8f6f4 v[72:75], v[24:31], v[208:215], v[72:75]
	v_mfma_f32_16x16x128_f8f6f4 v[60:63], v[16:23], v[216:223], v[60:63]
	v_mfma_f32_16x16x128_f8f6f4 v[56:59], v[24:31], v[216:223], v[56:59]
	v_mfma_f32_16x16x128_f8f6f4 v[44:47], v[16:23], v[224:231], v[44:47]
	v_mfma_f32_16x16x128_f8f6f4 v[40:43], v[24:31], v[224:231], v[40:43]
	s_setprio 0
	s_setprio 1
	v_mfma_f32_16x16x128_f8f6f4 v[84:87], v[0:7], v[200:207], v[84:87]
	v_mfma_f32_16x16x128_f8f6f4 v[80:83], v[8:15], v[200:207], v[80:83]
	v_mfma_f32_16x16x128_f8f6f4 v[68:71], v[0:7], v[208:215], v[68:71]
	v_mfma_f32_16x16x128_f8f6f4 v[64:67], v[8:15], v[208:215], v[64:67]
	v_mfma_f32_16x16x128_f8f6f4 v[52:55], v[0:7], v[216:223], v[52:55]
	v_mfma_f32_16x16x128_f8f6f4 v[48:51], v[8:15], v[216:223], v[48:51]
	v_mfma_f32_16x16x128_f8f6f4 v[36:39], v[0:7], v[224:231], v[36:39]
	v_mfma_f32_16x16x128_f8f6f4 v[32:35], v[8:15], v[224:231], v[32:35]
	s_setprio 0
	s_barrier
; #define PG8_STAGE(bufoff, gbase, voff) do { _Pragma("unroll") for (int _i = 0; _i < 2; ++_i) \
;         __builtin_amdgcn_global_load_lds((const unsigned*)((const char*)(gbase) + (voff)[_i]), (LAS unsigned*)(lds + (bufoff) + ldsw + _i * 8192), 16, 0, 0); } while (0)
; #define PG8_WAIT_V(n) asm volatile("s_waitcnt vmcnt(" #n ")" ::: "memory")
; #define PG8_WAIT_L(n) asm volatile("s_waitcnt lgkmcnt(" #n ")" ::: "memory")
; #define PG8_BAR __builtin_amdgcn_s_barrier()
; #define PG8_SCHED __builtin_amdgcn_sched_barrier(0)
; template <class Epi, class Sched, bool FP8 = false>
; __device__ __forceinline__ void gemm_phase(LAS unsigned char* lds, const Gemm g, const Sched& S, const Epi& E) {
;     ...
;             PG8_LDB(B0, 1, 0); PG8_LDB(B1, 1, 1); PG8_SCHED; PG8_LDA(At, 1, 0); PG8_STAGE(PG8_SA(0, 1), a2 + hstepA, voffA);
;             PG8_WAIT_V(8); PG8_WAIT_L(0); PG8_BAR; PG8_MMA(0, 0, At, B0); PG8_MMA(0, 1, At, B1); PG8_BAR; PG8_SCHED;
;             PG8_LDA(At, 1, 1); PG8_STAGE(PG8_SB(1, 0), b3, voffB); PG8_STAGE(PG8_SB(1, 1), b3 + hstepB, voffB); PG8_STAGE(PG8_SA(1, 0), a3, voffA);
;             PG8_WAIT_V(8); PG8_WAIT_L(0); PG8_BAR; PG8_MMA(1, 0, At, B0); PG8_MMA(1, 1, At, B1); PG8_BAR; PG8_SCHED;
;         }
	s_add_i32 s45, 0, 0x18000
	s_add_i32 s68, 0, 0x1c000
	v_add_u32_e32 v12, s45, v163
	v_add_u32_e32 v28, s68, v163
	ds_read_b128 v[0:3], v12
	ds_read_b128 v[4:7], v12 offset:1024
	ds_read_b128 v[8:11], v12 offset:2048
	ds_read_b128 v[12:15], v12 offset:3072
	ds_read_b128 v[16:19], v28
	ds_read_b128 v[20:23], v28 offset:1024
	ds_read_b128 v[24:27], v28 offset:2048
	ds_read_b128 v[28:31], v28 offset:3072
	s_add_u32 s42, s42, 0x40000
	s_addc_u32 s43, s43, 0
	s_mov_b32 m0, s50
	v_lshl_add_u64 v[232:233], s[42:43], 0, v[166:167]
	ds_read_b128 v[200:203], v194 offset:32768
	ds_read_b128 v[204:207], v194 offset:33792
	ds_read_b128 v[208:211], v194 offset:34816
	ds_read_b128 v[212:215], v194 offset:35840
	ds_read_b128 v[216:219], v194 offset:36864
	ds_read_b128 v[220:223], v194 offset:37888
	ds_read_b128 v[224:227], v194 offset:38912
	ds_read_b128 v[228:231], v194 offset:39936
	global_load_lds_dwordx4 v[232:233], off
	v_lshl_add_u64 v[232:233], s[42:43], 0, v[170:171]
	s_mov_b32 m0, s51
	s_nop 0
	global_load_lds_dwordx4 v[232:233], off
	s_waitcnt vmcnt(8)
	s_waitcnt lgkmcnt(0)
	s_barrier
	s_setprio 1
	s_waitcnt lgkmcnt(0)
	v_mfma_f32_16x16x128_f8f6f4 v[156:159], v[0:7], v[200:207], v[156:159]
	v_mfma_f32_16x16x128_f8f6f4 v[148:151], v[8:15], v[200:207], v[148:151]
	v_mfma_f32_16x16x128_f8f6f4 v[140:143], v[0:7], v[208:215], v[140:143]
	v_mfma_f32_16x16x128_f8f6f4 v[136:139], v[8:15], v[208:215], v[136:139]
	v_mfma_f32_16x16x128_f8f6f4 v[124:127], v[0:7], v[216:223], v[124:127]
	v_mfma_f32_16x16x128_f8f6f4 v[120:123], v[8:15], v[216:223], v[120:123]
	v_mfma_f32_16x16x128_f8f6f4 v[108:111], v[0:7], v[224:231], v[108:111]
	v_mfma_f32_16x16x128_f8f6f4 v[104:107], v[8:15], v[224:231], v[104:107]
	s_setprio 0
	s_setprio 1
	v_mfma_f32_16x16x128_f8f6f4 v[152:155], v[16:23], v[200:207], v[152:155]
	v_mfma_f32_16x16x128_f8f6f4 v[144:147], v[24:31], v[200:207], v[144:147]
	v_mfma_f32_16x16x128_f8f6f4 v[132:135], v[16:23], v[208:215], v[132:135]
	v_mfma_f32_16x16x128_f8f6f4 v[128:131], v[24:31], v[208:215], v[128:131]
	v_mfma_f32_16x16x128_f8f6f4 v[116:119], v[16:23], v[216:223], v[116:119]
	v_mfma_f32_16x16x128_f8f6f4 v[112:115], v[24:31], v[216:223], v[112:115]
	v_mfma_f32_16x16x128_f8f6f4 v[100:103], v[16:23], v[224:231], v[100:103]
	v_mfma_f32_16x16x128_f8f6f4 v[96:99], v[24:31], v[224:231], v[96:99]
	s_setprio 0
	s_barrier
	s_add_i32 s42, s45, s47
	v_lshl_add_u64 v[184:185], v[184:185], 0, s[22:23]
	s_mov_b32 m0, s42
	ds_read_b128 v[200:203], v194 offset:49152
	ds_read_b128 v[204:207], v194 offset:50176
	ds_read_b128 v[208:211], v194 offset:51200
	ds_read_b128 v[212:215], v194 offset:52224
	ds_read_b128 v[216:219], v194 offset:53248
	ds_read_b128 v[220:223], v194 offset:54272
	ds_read_b128 v[224:227], v194 offset:55296
	ds_read_b128 v[228:231], v194 offset:56320
	global_load_lds_dwordx4 v[184:185], off
	s_add_i32 m0, s42, 0x2000
	s_add_u32 s10, s10, 0x80080
	v_lshl_add_u64 v[184:185], v[186:187], 0, s[22:23]
	s_addc_u32 s11, s11, 0
	s_add_i32 s42, s68, s47
	global_load_lds_dwordx4 v[184:185], off
	v_lshl_add_u64 v[184:185], s[10:11], 0, v[168:169]
	s_mov_b32 m0, s42
	s_nop 0
	global_load_lds_dwordx4 v[184:185], off
	v_lshl_add_u64 v[184:185], s[10:11], 0, v[172:173]
	s_add_i32 m0, s42, 0x2000
	s_nop 0
	global_load_lds_dwordx4 v[184:185], off
	v_lshl_add_u64 v[184:185], v[188:189], 0, s[22:23]
	s_mov_b32 m0, s53
	s_nop 0
	global_load_lds_dwordx4 v[184:185], off
	v_lshl_add_u64 v[184:185], v[190:191], 0, s[22:23]
	s_mov_b32 m0, s54
	s_nop 0
	global_load_lds_dwordx4 v[184:185], off
	s_waitcnt vmcnt(8)
	s_waitcnt lgkmcnt(0)
	s_barrier
	s_setprio 1
	s_waitcnt lgkmcnt(0)
	v_mfma_f32_16x16x128_f8f6f4 v[92:95], v[0:7], v[200:207], v[92:95]
	v_mfma_f32_16x16x128_f8f6f4 v[88:91], v[8:15], v[200:207], v[88:91]
	v_mfma_f32_16x16x128_f8f6f4 v[76:79], v[0:7], v[208:215], v[76:79]
	v_mfma_f32_16x16x128_f8f6f4 v[72:75], v[8:15], v[208:215], v[72:75]
	v_mfma_f32_16x16x128_f8f6f4 v[60:63], v[0:7], v[216:223], v[60:63]
	v_mfma_f32_16x16x128_f8f6f4 v[56:59], v[8:15], v[216:223], v[56:59]
	v_mfma_f32_16x16x128_f8f6f4 v[44:47], v[0:7], v[224:231], v[44:47]
	v_mfma_f32_16x16x128_f8f6f4 v[40:43], v[8:15], v[224:231], v[40:43]
	s_setprio 0
	s_setprio 1
	v_mfma_f32_16x16x128_f8f6f4 v[84:87], v[16:23], v[200:207], v[84:87]
	v_mfma_f32_16x16x128_f8f6f4 v[80:83], v[24:31], v[200:207], v[80:83]
	v_mfma_f32_16x16x128_f8f6f4 v[68:71], v[16:23], v[208:215], v[68:71]
	v_mfma_f32_16x16x128_f8f6f4 v[64:67], v[24:31], v[208:215], v[64:67]
	v_mfma_f32_16x16x128_f8f6f4 v[52:55], v[16:23], v[216:223], v[52:55]
	v_mfma_f32_16x16x128_f8f6f4 v[48:51], v[24:31], v[216:223], v[48:51]
	v_mfma_f32_16x16x128_f8f6f4 v[36:39], v[16:23], v[224:231], v[36:39]
	v_mfma_f32_16x16x128_f8f6f4 v[32:35], v[24:31], v[224:231], v[32:35]
	s_setprio 0
	s_barrier
	s_add_i32 s44, s44, 2
	s_add_u32 s6, s6, 0x100
	s_addc_u32 s7, s7, 0
	s_add_u32 s35, s35, 0x100
	s_addc_u32 s37, s37, 0
	s_cmp_gt_u32 s44, 13
	s_cbranch_scc0 .LBB0_74
	s_and_b64 vcc, exec, s[24:25]
	s_cbranch_vccz .LBB0_77
	s_barrier

; #define PG8_STAGE(bufoff, gbase, voff) do { _Pragma("unroll") for (int _i = 0; _i < 2; ++_i) \
;         __builtin_amdgcn_global_load_lds((const unsigned*)((const char*)(gbase) + (voff)[_i]), (LAS unsigned*)(lds + (bufoff) + ldsw + _i * 8192), 16, 0, 0); } while (0)
; #define PG8_WAIT_V(n) asm volatile("s_waitcnt vmcnt(" #n ")" ::: "memory")
; #define PG8_WAIT_L(n) asm volatile("s_waitcnt lgkmcnt(" #n ")" ::: "memory")
; #define PG8_BAR __builtin_amdgcn_s_barrier()
; #define PG8_SCHED __builtin_amdgcn_sched_barrier(0)
; template <class Epi, class Sched, bool FP8 = false>
; __device__ __forceinline__ void gemm_phase(LAS unsigned char* lds, const Gemm g, const Sched& S, const Epi& E) {
;     ...
;             PG8_LDB(B0, 0, 0); PG8_LDB(B1, 0, 1); PG8_SCHED; PG8_LDA(At, 0, 0); PG8_STAGE(PG8_SA(1, 1), a1 + hstepA, voffA);
;             PG8_WAIT_V(8); PG8_WAIT_L(0); PG8_BAR; PG8_MMA(0, 0, At, B0); PG8_MMA(0, 1, At, B1); PG8_BAR; PG8_SCHED;
;             PG8_LDA(At, 0, 1); PG8_STAGE(PG8_SB(0, 0), b2, voffB); PG8_STAGE(PG8_SB(0, 1), b2 + hstepB, voffB); PG8_STAGE(PG8_SA(0, 0), a2, voffA);
;             PG8_WAIT_V(8); PG8_WAIT_L(0); PG8_BAR; PG8_MMA(1, 0, At, B0); PG8_MMA(1, 1, At, B1); PG8_BAR; PG8_SCHED;
.LBB0_418:
	v_add_u32_e32 v12, s40, v195
	v_add_u32_e32 v25, s41, v195
	ds_read_b128 v[0:3], v12
	ds_read_b128 v[4:7], v12 offset:1024
	ds_read_b128 v[8:11], v12 offset:2048
	ds_read_b128 v[12:15], v12 offset:3072
	ds_read_b128 v[16:19], v25
	ds_read_b128 v[20:23], v25 offset:1024
	ds_read_b128 v[200:203], v25 offset:2048
	ds_read_b128 v[204:207], v25 offset:3072
	s_add_i32 s55, s28, 2
	s_add_u32 s29, s26, 0xfffd0080
	s_addc_u32 s30, s27, -1
	s_cmp_eq_u32 s23, s28
	s_cselect_b32 s28, s24, s53
	s_cselect_b32 s31, s11, s30
	s_cselect_b32 s30, s10, s29
	s_cselect_b32 s29, s25, s54
	v_lshl_add_u64 v[26:27], s[26:27], 0, v[168:169]
	s_add_i32 m0, s33, 0xc000
	ds_read_b128 v[208:211], v197
	ds_read_b128 v[212:215], v197 offset:1024
	ds_read_b128 v[216:219], v197 offset:2048
	ds_read_b128 v[220:223], v197 offset:3072
	ds_read_b128 v[224:227], v197 offset:4096
	ds_read_b128 v[228:231], v197 offset:5120
	ds_read_b128 v[232:235], v197 offset:6144
	ds_read_b128 v[236:239], v197 offset:7168
	global_load_lds_dwordx4 v[26:27], off
	v_lshl_add_u64 v[26:27], s[26:27], 0, v[170:171]
	s_add_i32 m0, s33, 0xe000
	s_nop 0
	global_load_lds_dwordx4 v[26:27], off
	s_waitcnt vmcnt(8)
	s_waitcnt lgkmcnt(0)
	s_barrier
	s_setprio 1
	s_waitcnt lgkmcnt(0)
	v_mfma_f32_16x16x128_f8f6f4 v[152:155], v[0:7], v[208:215], v[152:155]
	v_mfma_f32_16x16x128_f8f6f4 v[148:151], v[8:15], v[208:215], v[148:151]
	v_mfma_f32_16x16x128_f8f6f4 v[144:147], v[0:7], v[216:223], v[144:147]
	v_mfma_f32_16x16x128_f8f6f4 v[140:143], v[8:15], v[216:223], v[140:143]
	v_mfma_f32_16x16x128_f8f6f4 v[136:139], v[0:7], v[224:231], v[136:139]
	v_mfma_f32_16x16x128_f8f6f4 v[132:135], v[8:15], v[224:231], v[132:135]
	v_mfma_f32_16x16x128_f8f6f4 v[128:131], v[0:7], v[232:239], v[128:131]
	v_mfma_f32_16x16x128_f8f6f4 v[124:127], v[8:15], v[232:239], v[124:127]
	s_setprio 0
	s_setprio 1
	v_mfma_f32_16x16x128_f8f6f4 v[120:123], v[16:23], v[208:215], v[120:123]
	v_mfma_f32_16x16x128_f8f6f4 v[116:119], v[200:207], v[208:215], v[116:119]
	v_mfma_f32_16x16x128_f8f6f4 v[112:115], v[16:23], v[216:223], v[112:115]
	v_mfma_f32_16x16x128_f8f6f4 v[108:111], v[200:207], v[216:223], v[108:111]
	v_mfma_f32_16x16x128_f8f6f4 v[104:107], v[16:23], v[224:231], v[104:107]
	v_mfma_f32_16x16x128_f8f6f4 v[100:103], v[200:207], v[224:231], v[100:103]
	v_mfma_f32_16x16x128_f8f6f4 v[96:99], v[16:23], v[232:239], v[96:99]
	v_mfma_f32_16x16x128_f8f6f4 v[92:95], v[200:207], v[232:239], v[92:95]
	s_setprio 0
	s_barrier
	s_add_i32 s56, s40, s19
	v_lshl_add_u64 v[26:27], s[28:29], 0, v[162:163]
	s_mov_b32 m0, s56
	ds_read_b128 v[208:211], v197 offset:16384
	ds_read_b128 v[212:215], v197 offset:17408
	ds_read_b128 v[216:219], v197 offset:18432
	ds_read_b128 v[220:223], v197 offset:19456
	ds_read_b128 v[224:227], v197 offset:20480
	ds_read_b128 v[228:231], v197 offset:21504
	ds_read_b128 v[232:235], v197 offset:22528
	ds_read_b128 v[236:239], v197 offset:23552
	global_load_lds_dwordx4 v[26:27], off
	s_add_i32 m0, s56, 0x2000
	s_add_u32 s56, s28, 0x30000
	v_lshl_add_u64 v[176:177], s[28:29], 0, v[166:167]
	s_addc_u32 s57, s29, 0
	s_add_i32 s58, s41, s19
	global_load_lds_dwordx4 v[176:177], off
	v_lshl_add_u64 v[178:179], s[56:57], 0, v[162:163]
	s_mov_b32 m0, s58
	v_lshl_add_u64 v[180:181], s[30:31], 0, v[164:165]
	global_load_lds_dwordx4 v[178:179], off
	v_lshl_add_u64 v[178:179], s[56:57], 0, v[166:167]
	s_add_i32 m0, s58, 0x2000
	s_nop 0
	global_load_lds_dwordx4 v[178:179], off
	v_lshl_add_u64 v[178:179], s[30:31], 0, v[158:159]
	s_mov_b32 m0, s33
	s_nop 0
	global_load_lds_dwordx4 v[178:179], off
	s_mov_b32 m0, s34
	s_nop 0
	global_load_lds_dwordx4 v[180:181], off
	s_waitcnt vmcnt(8)
	s_waitcnt lgkmcnt(0)
	s_barrier
	s_setprio 1
	s_waitcnt lgkmcnt(0)
	v_mfma_f32_16x16x128_f8f6f4 v[88:91], v[0:7], v[208:215], v[88:91]
	v_mfma_f32_16x16x128_f8f6f4 v[84:87], v[8:15], v[208:215], v[84:87]
	v_mfma_f32_16x16x128_f8f6f4 v[80:83], v[0:7], v[216:223], v[80:83]
	v_mfma_f32_16x16x128_f8f6f4 v[76:79], v[8:15], v[216:223], v[76:79]
	v_mfma_f32_16x16x128_f8f6f4 v[72:75], v[0:7], v[224:231], v[72:75]
	v_mfma_f32_16x16x128_f8f6f4 v[68:71], v[8:15], v[224:231], v[68:71]
	v_mfma_f32_16x16x128_f8f6f4 v[64:67], v[0:7], v[232:239], v[64:67]
	v_mfma_f32_16x16x128_f8f6f4 v[60:63], v[8:15], v[232:239], v[60:63]
	s_setprio 0
	s_setprio 1
	v_mfma_f32_16x16x128_f8f6f4 v[56:59], v[16:23], v[208:215], v[56:59]
	v_mfma_f32_16x16x128_f8f6f4 v[52:55], v[200:207], v[208:215], v[52:55]
	v_mfma_f32_16x16x128_f8f6f4 v[48:51], v[16:23], v[216:223], v[48:51]
	v_mfma_f32_16x16x128_f8f6f4 v[44:47], v[200:207], v[216:223], v[44:47]
	v_mfma_f32_16x16x128_f8f6f4 v[40:43], v[16:23], v[224:231], v[40:43]
	v_mfma_f32_16x16x128_f8f6f4 v[36:39], v[200:207], v[224:231], v[36:39]
	v_mfma_f32_16x16x128_f8f6f4 v[32:35], v[16:23], v[232:239], v[32:35]
	v_mfma_f32_16x16x128_f8f6f4 v[28:31], v[200:207], v[232:239], v[28:31]
	s_setprio 0
	s_barrier
; #define PG8_STAGE(bufoff, gbase, voff) do { _Pragma("unroll") for (int _i = 0; _i < 2; ++_i) \
;         __builtin_amdgcn_global_load_lds((const unsigned*)((const char*)(gbase) + (voff)[_i]), (LAS unsigned*)(lds + (bufoff) + ldsw + _i * 8192), 16, 0, 0); } while (0)
; #define PG8_WAIT_V(n) asm volatile("s_waitcnt vmcnt(" #n ")" ::: "memory")
; #define PG8_WAIT_L(n) asm volatile("s_waitcnt lgkmcnt(" #n ")" ::: "memory")
; #define PG8_BAR __builtin_amdgcn_s_barrier()
; #define PG8_SCHED __builtin_amdgcn_sched_barrier(0)
; template <class Epi, class Sched, bool FP8 = false>
; __device__ __forceinline__ void gemm_phase(LAS unsigned char* lds, const Gemm g, const Sched& S, const Epi& E) {
;     ...
;             PG8_LDB(B0, 1, 0); PG8_LDB(B1, 1, 1); PG8_SCHED; PG8_LDA(At, 1, 0); PG8_STAGE(PG8_SA(0, 1), a2 + hstepA, voffA);
;             PG8_WAIT_V(8); PG8_WAIT_L(0); PG8_BAR; PG8_MMA(0, 0, At, B0); PG8_MMA(0, 1, At, B1); PG8_BAR; PG8_SCHED;
;             PG8_LDA(At, 1, 1); PG8_STAGE(PG8_SB(1, 0), b3, voffB); PG8_STAGE(PG8_SB(1, 1), b3 + hstepB, voffB); PG8_STAGE(PG8_SA(1, 0), a3, voffA);
;             PG8_WAIT_V(8); PG8_WAIT_L(0); PG8_BAR; PG8_MMA(1, 0, At, B0); PG8_MMA(1, 1, At, B1); PG8_BAR; PG8_SCHED;
;         }
	s_add_i32 s56, 0, 0x18000
	s_add_i32 s57, 0, 0x1c000
	v_add_u32_e32 v0, s56, v195
	v_add_u32_e32 v20, s57, v195
	ds_read_b128 v[8:11], v0
	ds_read_b128 v[12:15], v0 offset:1024
	ds_read_b128 v[200:203], v0 offset:2048
	ds_read_b128 v[204:207], v0 offset:3072
	ds_read_b128 v[0:3], v20
	ds_read_b128 v[4:7], v20 offset:1024
	ds_read_b128 v[16:19], v20 offset:2048
	ds_read_b128 v[20:23], v20 offset:3072
	s_add_u32 s30, s30, 0x30000
	s_addc_u32 s31, s31, 0
	s_mov_b32 m0, s35
	v_lshl_add_u64 v[240:241], s[30:31], 0, v[158:159]
	ds_read_b128 v[208:211], v197 offset:32768
	ds_read_b128 v[212:215], v197 offset:33792
	ds_read_b128 v[216:219], v197 offset:34816
	ds_read_b128 v[220:223], v197 offset:35840
	ds_read_b128 v[224:227], v197 offset:36864
	ds_read_b128 v[228:231], v197 offset:37888
	ds_read_b128 v[232:235], v197 offset:38912
	ds_read_b128 v[236:239], v197 offset:39936
	global_load_lds_dwordx4 v[240:241], off
	v_lshl_add_u64 v[240:241], s[30:31], 0, v[164:165]
	s_mov_b32 m0, s36
	s_nop 0
	global_load_lds_dwordx4 v[240:241], off
	s_waitcnt vmcnt(8)
	s_waitcnt lgkmcnt(0)
	s_barrier
	s_setprio 1
	s_waitcnt lgkmcnt(0)
	v_mfma_f32_16x16x128_f8f6f4 v[152:155], v[8:15], v[208:215], v[152:155]
	v_mfma_f32_16x16x128_f8f6f4 v[148:151], v[200:207], v[208:215], v[148:151]
	v_mfma_f32_16x16x128_f8f6f4 v[144:147], v[8:15], v[216:223], v[144:147]
	v_mfma_f32_16x16x128_f8f6f4 v[140:143], v[200:207], v[216:223], v[140:143]
	v_mfma_f32_16x16x128_f8f6f4 v[136:139], v[8:15], v[224:231], v[136:139]
	v_mfma_f32_16x16x128_f8f6f4 v[132:135], v[200:207], v[224:231], v[132:135]
	v_mfma_f32_16x16x128_f8f6f4 v[128:131], v[8:15], v[232:239], v[128:131]
	v_mfma_f32_16x16x128_f8f6f4 v[124:127], v[200:207], v[232:239], v[124:127]
	s_setprio 0
	s_setprio 1
	v_mfma_f32_16x16x128_f8f6f4 v[120:123], v[0:7], v[208:215], v[120:123]
	v_mfma_f32_16x16x128_f8f6f4 v[116:119], v[16:23], v[208:215], v[116:119]
	v_mfma_f32_16x16x128_f8f6f4 v[112:115], v[0:7], v[216:223], v[112:115]
	v_mfma_f32_16x16x128_f8f6f4 v[108:111], v[16:23], v[216:223], v[108:111]
	v_mfma_f32_16x16x128_f8f6f4 v[104:107], v[0:7], v[224:231], v[104:107]
	v_mfma_f32_16x16x128_f8f6f4 v[100:103], v[16:23], v[224:231], v[100:103]
	v_mfma_f32_16x16x128_f8f6f4 v[96:99], v[0:7], v[232:239], v[96:99]
	v_mfma_f32_16x16x128_f8f6f4 v[92:95], v[16:23], v[232:239], v[92:95]
	s_setprio 0
	s_barrier
	s_add_i32 s30, s56, s19
	v_lshl_add_u64 v[26:27], v[26:27], 0, s[12:13]
	s_mov_b32 m0, s30
	ds_read_b128 v[208:211], v197 offset:49152
	ds_read_b128 v[212:215], v197 offset:50176
	ds_read_b128 v[216:219], v197 offset:51200
	ds_read_b128 v[220:223], v197 offset:52224
	ds_read_b128 v[224:227], v197 offset:53248
	ds_read_b128 v[228:231], v197 offset:54272
	ds_read_b128 v[232:235], v197 offset:55296
	ds_read_b128 v[236:239], v197 offset:56320
	global_load_lds_dwordx4 v[26:27], off
	s_add_i32 m0, s30, 0x2000
	s_add_u32 s28, s28, 0x30080
	v_lshl_add_u64 v[26:27], v[176:177], 0, s[12:13]
	s_addc_u32 s29, s29, 0
	s_add_i32 s30, s57, s19
	global_load_lds_dwordx4 v[26:27], off
	v_lshl_add_u64 v[26:27], s[28:29], 0, v[162:163]
	s_mov_b32 m0, s30
	s_nop 0
	global_load_lds_dwordx4 v[26:27], off
	v_lshl_add_u64 v[26:27], s[28:29], 0, v[166:167]
	s_add_i32 m0, s30, 0x2000
	s_nop 0
	global_load_lds_dwordx4 v[26:27], off
	v_lshl_add_u64 v[26:27], v[178:179], 0, s[12:13]
	s_mov_b32 m0, s38
	s_nop 0
	global_load_lds_dwordx4 v[26:27], off
	v_lshl_add_u64 v[26:27], v[180:181], 0, s[12:13]
	s_mov_b32 m0, s39
	s_nop 0
	global_load_lds_dwordx4 v[26:27], off
	s_waitcnt vmcnt(8)
	s_waitcnt lgkmcnt(0)
	s_barrier
	s_setprio 1
	s_waitcnt lgkmcnt(0)
	v_mfma_f32_16x16x128_f8f6f4 v[88:91], v[8:15], v[208:215], v[88:91]
	v_mfma_f32_16x16x128_f8f6f4 v[84:87], v[200:207], v[208:215], v[84:87]
	v_mfma_f32_16x16x128_f8f6f4 v[80:83], v[8:15], v[216:223], v[80:83]
	v_mfma_f32_16x16x128_f8f6f4 v[76:79], v[200:207], v[216:223], v[76:79]
	v_mfma_f32_16x16x128_f8f6f4 v[72:75], v[8:15], v[224:231], v[72:75]
	v_mfma_f32_16x16x128_f8f6f4 v[68:71], v[200:207], v[224:231], v[68:71]
	v_mfma_f32_16x16x128_f8f6f4 v[64:67], v[8:15], v[232:239], v[64:67]
	v_mfma_f32_16x16x128_f8f6f4 v[60:63], v[200:207], v[232:239], v[60:63]
	s_setprio 0
	s_setprio 1
	v_mfma_f32_16x16x128_f8f6f4 v[56:59], v[0:7], v[208:215], v[56:59]
	v_mfma_f32_16x16x128_f8f6f4 v[52:55], v[16:23], v[208:215], v[52:55]
	v_mfma_f32_16x16x128_f8f6f4 v[48:51], v[0:7], v[216:223], v[48:51]
	v_mfma_f32_16x16x128_f8f6f4 v[44:47], v[16:23], v[216:223], v[44:47]
	v_mfma_f32_16x16x128_f8f6f4 v[40:43], v[0:7], v[224:231], v[40:43]
	v_mfma_f32_16x16x128_f8f6f4 v[36:39], v[16:23], v[224:231], v[36:39]
	v_mfma_f32_16x16x128_f8f6f4 v[32:35], v[0:7], v[232:239], v[32:35]
	v_mfma_f32_16x16x128_f8f6f4 v[28:31], v[16:23], v[232:239], v[28:31]
	s_setprio 0
	s_barrier
	s_add_u32 s26, s26, 0x100
	s_addc_u32 s27, s27, 0
	s_add_u32 s53, s53, 0x100
	s_addc_u32 s54, s54, 0
	s_cmp_ge_i32 s55, s50
	s_mov_b32 s28, s55
	s_cbranch_scc0 .LBB0_418
	s_and_b64 vcc, exec, s[14:15]
	s_cbranch_vccz .LBB0_421
	s_barrier

; #define PG8_STAGE(bufoff, gbase, voff) do { _Pragma("unroll") for (int _i = 0; _i < 2; ++_i) \
;         __builtin_amdgcn_global_load_lds((const unsigned*)((const char*)(gbase) + (voff)[_i]), (LAS unsigned*)(lds + (bufoff) + ldsw + _i * 8192), 16, 0, 0); } while (0)
; #define PG8_WAIT_V(n) asm volatile("s_waitcnt vmcnt(" #n ")" ::: "memory")
; #define PG8_WAIT_L(n) asm volatile("s_waitcnt lgkmcnt(" #n ")" ::: "memory")
; #define PG8_BAR __builtin_amdgcn_s_barrier()
; #define PG8_SCHED __builtin_amdgcn_sched_barrier(0)
; template <class Epi, class Sched, bool FP8 = false>
; __device__ __forceinline__ void gemm_phase(LAS unsigned char* lds, const Gemm g, const Sched& S, const Epi& E) {
;     ...
;             PG8_LDB(B0, 0, 0); PG8_LDB(B1, 0, 1); PG8_SCHED; PG8_LDA(At, 0, 0); PG8_STAGE(PG8_SA(1, 1), a1 + hstepA, voffA);
;             PG8_WAIT_V(8); PG8_WAIT_L(0); PG8_BAR; PG8_MMA(0, 0, At, B0); PG8_MMA(0, 1, At, B1); PG8_BAR; PG8_SCHED;
;             PG8_LDA(At, 0, 1); PG8_STAGE(PG8_SB(0, 0), b2, voffB); PG8_STAGE(PG8_SB(0, 1), b2 + hstepB, voffB); PG8_STAGE(PG8_SA(0, 0), a2, voffA);
;             PG8_WAIT_V(8); PG8_WAIT_L(0); PG8_BAR; PG8_MMA(1, 0, At, B0); PG8_MMA(1, 1, At, B1); PG8_BAR; PG8_SCHED;
.LBB0_476:
	ds_read_b128 v[16:19], v190
	ds_read_b128 v[20:23], v190 offset:1024
	ds_read_b128 v[24:27], v190 offset:2048
	ds_read_b128 v[28:31], v190 offset:3072
	ds_read_b128 v[0:3], v191
	s_waitcnt lgkmcnt(0)
	ds_read_b128 v[4:7], v191 offset:1024
	ds_read_b128 v[8:11], v191 offset:2048
	ds_read_b128 v[12:15], v191 offset:3072
	s_add_u32 s36, s34, 0xfffc0080
	s_addc_u32 s37, s35, -1
	s_cmp_eq_u32 s51, 12
	s_cselect_b32 s39, s7, s37
	s_cselect_b32 s38, s27, s36
	s_cselect_b32 s37, s25, s50
	s_cselect_b32 s36, s48, s49
	v_lshl_add_u64 v[220:221], s[34:35], 0, v[160:161]
	s_add_i32 m0, s23, 0xc000
	ds_read_b128 v[178:181], v193
	ds_read_b128 v[182:185], v193 offset:1024
	ds_read_b128 v[196:199], v193 offset:2048
	ds_read_b128 v[200:203], v193 offset:3072
	ds_read_b128 v[204:207], v193 offset:4096
	ds_read_b128 v[208:211], v193 offset:5120
	ds_read_b128 v[212:215], v193 offset:6144
	ds_read_b128 v[216:219], v193 offset:7168
	global_load_lds_dwordx4 v[220:221], off
	v_lshl_add_u64 v[220:221], s[34:35], 0, v[172:173]
	s_add_i32 m0, s23, 0xe000
	s_nop 0
	global_load_lds_dwordx4 v[220:221], off
	s_waitcnt vmcnt(8)
	s_waitcnt lgkmcnt(0)
	s_barrier
	s_setprio 1
	s_waitcnt lgkmcnt(0)
	v_mfma_f32_16x16x128_f8f6f4 v[156:159], v[16:23], v[178:185], v[156:159]
	v_mfma_f32_16x16x128_f8f6f4 v[152:155], v[24:31], v[178:185], v[152:155]
	v_mfma_f32_16x16x128_f8f6f4 v[140:143], v[16:23], v[196:203], v[140:143]
	v_mfma_f32_16x16x128_f8f6f4 v[136:139], v[24:31], v[196:203], v[136:139]
	v_mfma_f32_16x16x128_f8f6f4 v[124:127], v[16:23], v[204:211], v[124:127]
	v_mfma_f32_16x16x128_f8f6f4 v[120:123], v[24:31], v[204:211], v[120:123]
	v_mfma_f32_16x16x128_f8f6f4 v[108:111], v[16:23], v[212:219], v[108:111]
	v_mfma_f32_16x16x128_f8f6f4 v[104:107], v[24:31], v[212:219], v[104:107]
	s_setprio 0
	s_setprio 1
	v_mfma_f32_16x16x128_f8f6f4 v[148:151], v[0:7], v[178:185], v[148:151]
	v_mfma_f32_16x16x128_f8f6f4 v[144:147], v[8:15], v[178:185], v[144:147]
	v_mfma_f32_16x16x128_f8f6f4 v[132:135], v[0:7], v[196:203], v[132:135]
	v_mfma_f32_16x16x128_f8f6f4 v[128:131], v[8:15], v[196:203], v[128:131]
	v_mfma_f32_16x16x128_f8f6f4 v[116:119], v[0:7], v[204:211], v[116:119]
	v_mfma_f32_16x16x128_f8f6f4 v[112:115], v[8:15], v[204:211], v[112:115]
	v_mfma_f32_16x16x128_f8f6f4 v[100:103], v[0:7], v[212:219], v[100:103]
	v_mfma_f32_16x16x128_f8f6f4 v[96:99], v[8:15], v[212:219], v[96:99]
	s_setprio 0
	s_barrier
	s_add_i32 s52, s45, s21
	v_lshl_add_u64 v[178:179], s[36:37], 0, v[164:165]
	s_mov_b32 m0, s52
	ds_read_b128 v[196:199], v193 offset:16384
	ds_read_b128 v[200:203], v193 offset:17408
	ds_read_b128 v[204:207], v193 offset:18432
	ds_read_b128 v[208:211], v193 offset:19456
	ds_read_b128 v[212:215], v193 offset:20480
	ds_read_b128 v[216:219], v193 offset:21504
	ds_read_b128 v[220:223], v193 offset:22528
	ds_read_b128 v[224:227], v193 offset:23552
	global_load_lds_dwordx4 v[178:179], off
	s_add_i32 m0, s52, 0x2000
	s_add_u32 s52, s36, 0x40000
	v_lshl_add_u64 v[180:181], s[36:37], 0, v[168:169]
	s_addc_u32 s53, s37, 0
	s_add_i32 s54, s46, s21
	global_load_lds_dwordx4 v[180:181], off
	v_lshl_add_u64 v[182:183], s[52:53], 0, v[164:165]
	s_mov_b32 m0, s54
	v_lshl_add_u64 v[184:185], s[38:39], 0, v[166:167]
	global_load_lds_dwordx4 v[182:183], off
	v_lshl_add_u64 v[182:183], s[52:53], 0, v[168:169]
	s_add_i32 m0, s54, 0x2000
	s_nop 0
	global_load_lds_dwordx4 v[182:183], off
	v_lshl_add_u64 v[182:183], s[38:39], 0, v[162:163]
	s_mov_b32 m0, s23
	s_nop 0
	global_load_lds_dwordx4 v[182:183], off
	s_mov_b32 m0, s33
	s_nop 0
	global_load_lds_dwordx4 v[184:185], off
	s_waitcnt vmcnt(8)
	s_waitcnt lgkmcnt(0)
	s_barrier
	s_setprio 1
	s_waitcnt lgkmcnt(0)
	v_mfma_f32_16x16x128_f8f6f4 v[92:95], v[16:23], v[196:203], v[92:95]
	v_mfma_f32_16x16x128_f8f6f4 v[88:91], v[24:31], v[196:203], v[88:91]
	v_mfma_f32_16x16x128_f8f6f4 v[76:79], v[16:23], v[204:211], v[76:79]
	v_mfma_f32_16x16x128_f8f6f4 v[72:75], v[24:31], v[204:211], v[72:75]
	v_mfma_f32_16x16x128_f8f6f4 v[60:63], v[16:23], v[212:219], v[60:63]
	v_mfma_f32_16x16x128_f8f6f4 v[56:59], v[24:31], v[212:219], v[56:59]
	v_mfma_f32_16x16x128_f8f6f4 v[44:47], v[16:23], v[220:227], v[44:47]
	v_mfma_f32_16x16x128_f8f6f4 v[40:43], v[24:31], v[220:227], v[40:43]
	s_setprio 0
	s_setprio 1
	v_mfma_f32_16x16x128_f8f6f4 v[84:87], v[0:7], v[196:203], v[84:87]
	v_mfma_f32_16x16x128_f8f6f4 v[80:83], v[8:15], v[196:203], v[80:83]
	v_mfma_f32_16x16x128_f8f6f4 v[68:71], v[0:7], v[204:211], v[68:71]
	v_mfma_f32_16x16x128_f8f6f4 v[64:67], v[8:15], v[204:211], v[64:67]
	v_mfma_f32_16x16x128_f8f6f4 v[52:55], v[0:7], v[212:219], v[52:55]
	v_mfma_f32_16x16x128_f8f6f4 v[48:51], v[8:15], v[212:219], v[48:51]
	v_mfma_f32_16x16x128_f8f6f4 v[36:39], v[0:7], v[220:227], v[36:39]
	v_mfma_f32_16x16x128_f8f6f4 v[32:35], v[8:15], v[220:227], v[32:35]
	s_setprio 0
	s_barrier
; #define PG8_STAGE(bufoff, gbase, voff) do { _Pragma("unroll") for (int _i = 0; _i < 2; ++_i) \
;         __builtin_amdgcn_global_load_lds((const unsigned*)((const char*)(gbase) + (voff)[_i]), (LAS unsigned*)(lds + (bufoff) + ldsw + _i * 8192), 16, 0, 0); } while (0)
; #define PG8_WAIT_V(n) asm volatile("s_waitcnt vmcnt(" #n ")" ::: "memory")
; #define PG8_WAIT_L(n) asm volatile("s_waitcnt lgkmcnt(" #n ")" ::: "memory")
; #define PG8_BAR __builtin_amdgcn_s_barrier()
; #define PG8_SCHED __builtin_amdgcn_sched_barrier(0)
; template <class Epi, class Sched, bool FP8 = false>
; __device__ __forceinline__ void gemm_phase(LAS unsigned char* lds, const Gemm g, const Sched& S, const Epi& E) {
;     ...
;             PG8_LDB(B0, 1, 0); PG8_LDB(B1, 1, 1); PG8_SCHED; PG8_LDA(At, 1, 0); PG8_STAGE(PG8_SA(0, 1), a2 + hstepA, voffA);
;             PG8_WAIT_V(8); PG8_WAIT_L(0); PG8_BAR; PG8_MMA(0, 0, At, B0); PG8_MMA(0, 1, At, B1); PG8_BAR; PG8_SCHED;
;             PG8_LDA(At, 1, 1); PG8_STAGE(PG8_SB(1, 0), b3, voffB); PG8_STAGE(PG8_SB(1, 1), b3 + hstepB, voffB); PG8_STAGE(PG8_SA(1, 0), a3, voffA);
;             PG8_WAIT_V(8); PG8_WAIT_L(0); PG8_BAR; PG8_MMA(1, 0, At, B0); PG8_MMA(1, 1, At, B1); PG8_BAR; PG8_SCHED;
;         }
	s_add_i32 s52, 0, 0x18000
	s_add_i32 s53, 0, 0x1c000
	v_add_u32_e32 v12, s52, v187
	v_add_u32_e32 v28, s53, v187
	ds_read_b128 v[0:3], v12
	ds_read_b128 v[4:7], v12 offset:1024
	ds_read_b128 v[8:11], v12 offset:2048
	ds_read_b128 v[12:15], v12 offset:3072
	ds_read_b128 v[16:19], v28
	ds_read_b128 v[20:23], v28 offset:1024
	ds_read_b128 v[24:27], v28 offset:2048
	ds_read_b128 v[28:31], v28 offset:3072
	s_add_u32 s38, s38, 0x40000
	s_addc_u32 s39, s39, 0
	s_mov_b32 m0, s40
	v_lshl_add_u64 v[228:229], s[38:39], 0, v[162:163]
	ds_read_b128 v[196:199], v193 offset:32768
	ds_read_b128 v[200:203], v193 offset:33792
	ds_read_b128 v[204:207], v193 offset:34816
	ds_read_b128 v[208:211], v193 offset:35840
	ds_read_b128 v[212:215], v193 offset:36864
	ds_read_b128 v[216:219], v193 offset:37888
	ds_read_b128 v[220:223], v193 offset:38912
	ds_read_b128 v[224:227], v193 offset:39936
	global_load_lds_dwordx4 v[228:229], off
	v_lshl_add_u64 v[228:229], s[38:39], 0, v[166:167]
	s_mov_b32 m0, s41
	s_nop 0
	global_load_lds_dwordx4 v[228:229], off
	s_waitcnt vmcnt(8)
	s_waitcnt lgkmcnt(0)
	s_barrier
	s_setprio 1
	s_waitcnt lgkmcnt(0)
	v_mfma_f32_16x16x128_f8f6f4 v[156:159], v[0:7], v[196:203], v[156:159]
	v_mfma_f32_16x16x128_f8f6f4 v[152:155], v[8:15], v[196:203], v[152:155]
	v_mfma_f32_16x16x128_f8f6f4 v[140:143], v[0:7], v[204:211], v[140:143]
	v_mfma_f32_16x16x128_f8f6f4 v[136:139], v[8:15], v[204:211], v[136:139]
	v_mfma_f32_16x16x128_f8f6f4 v[124:127], v[0:7], v[212:219], v[124:127]
	v_mfma_f32_16x16x128_f8f6f4 v[120:123], v[8:15], v[212:219], v[120:123]
	v_mfma_f32_16x16x128_f8f6f4 v[108:111], v[0:7], v[220:227], v[108:111]
	v_mfma_f32_16x16x128_f8f6f4 v[104:107], v[8:15], v[220:227], v[104:107]
	s_setprio 0
	s_setprio 1
	v_mfma_f32_16x16x128_f8f6f4 v[148:151], v[16:23], v[196:203], v[148:151]
	v_mfma_f32_16x16x128_f8f6f4 v[144:147], v[24:31], v[196:203], v[144:147]
	v_mfma_f32_16x16x128_f8f6f4 v[132:135], v[16:23], v[204:211], v[132:135]
	v_mfma_f32_16x16x128_f8f6f4 v[128:131], v[24:31], v[204:211], v[128:131]
	v_mfma_f32_16x16x128_f8f6f4 v[116:119], v[16:23], v[212:219], v[116:119]
	v_mfma_f32_16x16x128_f8f6f4 v[112:115], v[24:31], v[212:219], v[112:115]
	v_mfma_f32_16x16x128_f8f6f4 v[100:103], v[16:23], v[220:227], v[100:103]
	v_mfma_f32_16x16x128_f8f6f4 v[96:99], v[24:31], v[220:227], v[96:99]
	s_setprio 0
	s_barrier
	s_add_i32 s38, s52, s21
	v_lshl_add_u64 v[178:179], v[178:179], 0, s[16:17]
	s_mov_b32 m0, s38
	ds_read_b128 v[196:199], v193 offset:49152
	ds_read_b128 v[200:203], v193 offset:50176
	ds_read_b128 v[204:207], v193 offset:51200
	ds_read_b128 v[208:211], v193 offset:52224
	ds_read_b128 v[212:215], v193 offset:53248
	ds_read_b128 v[216:219], v193 offset:54272
	ds_read_b128 v[220:223], v193 offset:55296
	ds_read_b128 v[224:227], v193 offset:56320
	global_load_lds_dwordx4 v[178:179], off
	s_add_i32 m0, s38, 0x2000
	s_add_u32 s36, s36, 0x40080
	v_lshl_add_u64 v[178:179], v[180:181], 0, s[16:17]
	s_addc_u32 s37, s37, 0
	s_add_i32 s38, s53, s21
	global_load_lds_dwordx4 v[178:179], off
	v_lshl_add_u64 v[178:179], s[36:37], 0, v[164:165]
	s_mov_b32 m0, s38
	s_nop 0
	global_load_lds_dwordx4 v[178:179], off
	v_lshl_add_u64 v[178:179], s[36:37], 0, v[168:169]
	s_add_i32 m0, s38, 0x2000
	s_nop 0
	global_load_lds_dwordx4 v[178:179], off
	v_lshl_add_u64 v[178:179], v[182:183], 0, s[16:17]
	s_mov_b32 m0, s43
	s_nop 0
	global_load_lds_dwordx4 v[178:179], off
	v_lshl_add_u64 v[178:179], v[184:185], 0, s[16:17]
	s_mov_b32 m0, s44
	s_nop 0
	global_load_lds_dwordx4 v[178:179], off
	s_waitcnt vmcnt(8)
	s_waitcnt lgkmcnt(0)
	s_barrier
	s_setprio 1
	s_waitcnt lgkmcnt(0)
	v_mfma_f32_16x16x128_f8f6f4 v[92:95], v[0:7], v[196:203], v[92:95]
	v_mfma_f32_16x16x128_f8f6f4 v[88:91], v[8:15], v[196:203], v[88:91]
	v_mfma_f32_16x16x128_f8f6f4 v[76:79], v[0:7], v[204:211], v[76:79]
	v_mfma_f32_16x16x128_f8f6f4 v[72:75], v[8:15], v[204:211], v[72:75]
	v_mfma_f32_16x16x128_f8f6f4 v[60:63], v[0:7], v[212:219], v[60:63]
	v_mfma_f32_16x16x128_f8f6f4 v[56:59], v[8:15], v[212:219], v[56:59]
	v_mfma_f32_16x16x128_f8f6f4 v[44:47], v[0:7], v[220:227], v[44:47]
	v_mfma_f32_16x16x128_f8f6f4 v[40:43], v[8:15], v[220:227], v[40:43]
	s_setprio 0
	s_setprio 1
	v_mfma_f32_16x16x128_f8f6f4 v[84:87], v[16:23], v[196:203], v[84:87]
	v_mfma_f32_16x16x128_f8f6f4 v[80:83], v[24:31], v[196:203], v[80:83]
	v_mfma_f32_16x16x128_f8f6f4 v[68:71], v[16:23], v[204:211], v[68:71]
	v_mfma_f32_16x16x128_f8f6f4 v[64:67], v[24:31], v[204:211], v[64:67]
	v_mfma_f32_16x16x128_f8f6f4 v[52:55], v[16:23], v[212:219], v[52:55]
	v_mfma_f32_16x16x128_f8f6f4 v[48:51], v[24:31], v[212:219], v[48:51]
	v_mfma_f32_16x16x128_f8f6f4 v[36:39], v[16:23], v[220:227], v[36:39]
	v_mfma_f32_16x16x128_f8f6f4 v[32:35], v[24:31], v[220:227], v[32:35]
	s_setprio 0
	s_barrier
	s_add_i32 s51, s51, 2
	s_add_u32 s34, s34, 0x100
	s_addc_u32 s35, s35, 0
	s_add_u32 s49, s49, 0x100
	s_addc_u32 s50, s50, 0
	s_cmp_gt_u32 s51, 13
	s_cbranch_scc0 .LBB0_476
	s_and_b64 vcc, exec, s[18:19]
	s_cbranch_vccz .LBB0_479
	s_barrier
